# follow-on units skip the 128 accumulator moves (first-touch MFMAs take C=0); barrier census loads in flight; swa query rows pre-touched
# speedup vs baseline: 1.0068x; 1.0032x over previous
.LBB0_149:
	s_add_i32 s34, s19, -2
	s_add_u32 s92, s92, 0x80
	s_addc_u32 s93, s93, 0
	s_add_u32 s96, s94, 0x100
	s_addc_u32 s97, s95, 0
	s_mov_b32 s94, 0
	s_cmp_lt_u32 s59, 2
	s_cbranch_scc1 .Lkloop_zero
	s_add_i32 vcc_lo, s94, 2
	s_add_u32 s82, s92, 0x80
	s_addc_u32 s83, s93, 0
	s_add_i32 vcc_hi, 0, 0x10000
	s_cmp_eq_u32 s34, s94
	s_cselect_b32 s95, s89, s83
	s_cselect_b32 s94, s88, s82
	v_add_u32_e32 v136, vcc_hi, v176
	s_cselect_b32 s83, s91, s97
	s_cselect_b32 s82, s90, s96
	s_add_i32 s7, 0, 0x14000
	s_waitcnt lgkmcnt(0)
	ds_read_b128 v[128:131], v136
	ds_read_b128 v[132:135], v136 offset:1024
	ds_read_b128 v[152:155], v136 offset:2048
	ds_read_b128 v[156:159], v136 offset:3072
	v_add_u32_e32 v136, s7, v176
	ds_read_b128 v[180:183], v136
	ds_read_b128 v[184:187], v136 offset:1024
	ds_read_b128 v[188:191], v136 offset:2048
	ds_read_b128 v[192:195], v136 offset:3072
	v_lshl_add_u64 v[160:161], s[92:93], 0, v[148:149]
	s_add_i32 m0, s52, 0xc000
	ds_read_b128 v[196:199], v178
	ds_read_b128 v[200:203], v178 offset:1024
	ds_read_b128 v[204:207], v178 offset:2048
	ds_read_b128 v[208:211], v178 offset:3072
	ds_read_b128 v[212:215], v178 offset:4096
	ds_read_b128 v[216:219], v178 offset:5120
	ds_read_b128 v[220:223], v178 offset:6144
	ds_read_b128 v[224:227], v178 offset:7168
	global_load_lds_dwordx4 v[160:161], off
	v_lshl_add_u64 v[160:161], s[92:93], 0, v[150:151]
	s_add_i32 m0, s52, 0xe000
	s_nop 0
	global_load_lds_dwordx4 v[160:161], off
	s_waitcnt vmcnt(24)
	s_waitcnt lgkmcnt(0)
	s_barrier
	s_setprio 1
	s_waitcnt lgkmcnt(0)
	v_mfma_f32_16x16x32_bf16 v[124:127], v[128:131], v[196:199], 0
	v_mfma_f32_16x16x32_bf16 v[120:123], v[152:155], v[196:199], 0
	v_mfma_f32_16x16x32_bf16 v[108:111], v[128:131], v[204:207], 0
	v_mfma_f32_16x16x32_bf16 v[104:107], v[152:155], v[204:207], 0
	v_mfma_f32_16x16x32_bf16 v[92:95], v[128:131], v[212:215], 0
	v_mfma_f32_16x16x32_bf16 v[88:91], v[152:155], v[212:215], 0
	v_mfma_f32_16x16x32_bf16 v[76:79], v[128:131], v[220:223], 0
	v_mfma_f32_16x16x32_bf16 v[72:75], v[152:155], v[220:223], 0
	v_mfma_f32_16x16x32_bf16 v[124:127], v[132:135], v[200:203], v[124:127]
	v_mfma_f32_16x16x32_bf16 v[120:123], v[156:159], v[200:203], v[120:123]
	v_mfma_f32_16x16x32_bf16 v[108:111], v[132:135], v[208:211], v[108:111]
	v_mfma_f32_16x16x32_bf16 v[104:107], v[156:159], v[208:211], v[104:107]
	v_mfma_f32_16x16x32_bf16 v[92:95], v[132:135], v[216:219], v[92:95]
	v_mfma_f32_16x16x32_bf16 v[88:91], v[156:159], v[216:219], v[88:91]
	v_mfma_f32_16x16x32_bf16 v[76:79], v[132:135], v[224:227], v[76:79]
	v_mfma_f32_16x16x32_bf16 v[72:75], v[156:159], v[224:227], v[72:75]
	s_setprio 0
	s_setprio 1
	v_mfma_f32_16x16x32_bf16 v[116:119], v[180:183], v[196:199], 0
	v_mfma_f32_16x16x32_bf16 v[112:115], v[188:191], v[196:199], 0
	v_mfma_f32_16x16x32_bf16 v[100:103], v[180:183], v[204:207], 0
	v_mfma_f32_16x16x32_bf16 v[96:99], v[188:191], v[204:207], 0
	v_mfma_f32_16x16x32_bf16 v[84:87], v[180:183], v[212:215], 0
	v_mfma_f32_16x16x32_bf16 v[80:83], v[188:191], v[212:215], 0
	v_mfma_f32_16x16x32_bf16 v[68:71], v[180:183], v[220:223], 0
	v_mfma_f32_16x16x32_bf16 v[64:67], v[188:191], v[220:223], 0
	v_mfma_f32_16x16x32_bf16 v[116:119], v[184:187], v[200:203], v[116:119]
	v_mfma_f32_16x16x32_bf16 v[112:115], v[192:195], v[200:203], v[112:115]
	v_mfma_f32_16x16x32_bf16 v[100:103], v[184:187], v[208:211], v[100:103]
	v_mfma_f32_16x16x32_bf16 v[96:99], v[192:195], v[208:211], v[96:99]
	v_mfma_f32_16x16x32_bf16 v[84:87], v[184:187], v[216:219], v[84:87]
	v_mfma_f32_16x16x32_bf16 v[80:83], v[192:195], v[216:219], v[80:83]
	v_mfma_f32_16x16x32_bf16 v[68:71], v[184:187], v[224:227], v[68:71]
	v_mfma_f32_16x16x32_bf16 v[64:67], v[192:195], v[224:227], v[64:67]
	s_setprio 0
	s_barrier
	s_add_i32 vcc_hi, vcc_hi, s51
	v_lshl_add_u64 v[160:161], s[82:83], 0, v[140:141]
	s_mov_b32 m0, vcc_hi
	ds_read_b128 v[196:199], v178 offset:16384
	ds_read_b128 v[200:203], v178 offset:17408
	ds_read_b128 v[204:207], v178 offset:18432
	ds_read_b128 v[208:211], v178 offset:19456
	ds_read_b128 v[212:215], v178 offset:20480
	ds_read_b128 v[216:219], v178 offset:21504
	ds_read_b128 v[220:223], v178 offset:22528
	ds_read_b128 v[224:227], v178 offset:23552
	global_load_lds_dwordx4 v[160:161], off
	s_add_i32 m0, vcc_hi, 0x2000
	v_lshl_add_u64 v[228:229], s[82:83], 0, v[144:145]
	s_add_u32 s82, s82, s2
	s_addc_u32 s83, s83, s3
	s_add_i32 s7, s7, s51
	global_load_lds_dwordx4 v[228:229], off
	v_lshl_add_u64 v[230:231], s[82:83], 0, v[140:141]
	s_mov_b32 m0, s7
	v_lshl_add_u64 v[232:233], s[82:83], 0, v[144:145]
	global_load_lds_dwordx4 v[230:231], off
	s_add_i32 m0, s7, 0x2000
	v_lshl_add_u64 v[234:235], s[94:95], 0, v[138:139]
	global_load_lds_dwordx4 v[232:233], off
	s_mov_b32 m0, s52
	v_lshl_add_u64 v[236:237], s[94:95], 0, v[142:143]
	global_load_lds_dwordx4 v[234:235], off
	s_mov_b32 m0, s53
	s_nop 0
	global_load_lds_dwordx4 v[236:237], off
	s_waitcnt vmcnt(24)
	s_waitcnt lgkmcnt(0)
	s_barrier
	s_setprio 1
	s_waitcnt lgkmcnt(0)
	v_mfma_f32_16x16x32_bf16 v[60:63], v[128:131], v[196:199], 0
	v_mfma_f32_16x16x32_bf16 v[56:59], v[152:155], v[196:199], 0
	v_mfma_f32_16x16x32_bf16 v[44:47], v[128:131], v[204:207], 0
	v_mfma_f32_16x16x32_bf16 v[40:43], v[152:155], v[204:207], 0
	v_mfma_f32_16x16x32_bf16 v[28:31], v[128:131], v[212:215], 0
	v_mfma_f32_16x16x32_bf16 v[24:27], v[152:155], v[212:215], 0
	v_mfma_f32_16x16x32_bf16 v[12:15], v[128:131], v[220:223], 0
	v_mfma_f32_16x16x32_bf16 v[8:11], v[152:155], v[220:223], 0
	v_mfma_f32_16x16x32_bf16 v[60:63], v[132:135], v[200:203], v[60:63]
	v_mfma_f32_16x16x32_bf16 v[56:59], v[156:159], v[200:203], v[56:59]
	v_mfma_f32_16x16x32_bf16 v[44:47], v[132:135], v[208:211], v[44:47]
	v_mfma_f32_16x16x32_bf16 v[40:43], v[156:159], v[208:211], v[40:43]
	v_mfma_f32_16x16x32_bf16 v[28:31], v[132:135], v[216:219], v[28:31]
	v_mfma_f32_16x16x32_bf16 v[24:27], v[156:159], v[216:219], v[24:27]
	v_mfma_f32_16x16x32_bf16 v[12:15], v[132:135], v[224:227], v[12:15]
	v_mfma_f32_16x16x32_bf16 v[8:11], v[156:159], v[224:227], v[8:11]
	s_setprio 0
	s_setprio 1
	v_mfma_f32_16x16x32_bf16 v[52:55], v[180:183], v[196:199], 0
	v_mfma_f32_16x16x32_bf16 v[48:51], v[188:191], v[196:199], 0
	v_mfma_f32_16x16x32_bf16 v[36:39], v[180:183], v[204:207], 0
	v_mfma_f32_16x16x32_bf16 v[32:35], v[188:191], v[204:207], 0
	v_mfma_f32_16x16x32_bf16 v[20:23], v[180:183], v[212:215], 0
	v_mfma_f32_16x16x32_bf16 v[16:19], v[188:191], v[212:215], 0
	v_mfma_f32_16x16x32_bf16 v[4:7], v[180:183], v[220:223], 0
	v_mfma_f32_16x16x32_bf16 v[0:3], v[188:191], v[220:223], 0
	v_mfma_f32_16x16x32_bf16 v[52:55], v[184:187], v[200:203], v[52:55]
	v_mfma_f32_16x16x32_bf16 v[48:51], v[192:195], v[200:203], v[48:51]
	v_mfma_f32_16x16x32_bf16 v[36:39], v[184:187], v[208:211], v[36:39]
	v_mfma_f32_16x16x32_bf16 v[32:35], v[192:195], v[208:211], v[32:35]
	v_mfma_f32_16x16x32_bf16 v[20:23], v[184:187], v[216:219], v[20:23]
	v_mfma_f32_16x16x32_bf16 v[16:19], v[192:195], v[216:219], v[16:19]
	v_mfma_f32_16x16x32_bf16 v[4:7], v[184:187], v[224:227], v[4:7]
	v_mfma_f32_16x16x32_bf16 v[0:3], v[192:195], v[224:227], v[0:3]
	s_setprio 0
	s_barrier
	s_add_i32 s7, 0, 0x18000
	v_add_u32_e32 v136, s7, v176
	s_add_i32 vcc_hi, 0, 0x1c000
	ds_read_b128 v[128:131], v136
	ds_read_b128 v[132:135], v136 offset:1024
	ds_read_b128 v[152:155], v136 offset:2048
	ds_read_b128 v[156:159], v136 offset:3072
	v_add_u32_e32 v136, vcc_hi, v176
	ds_read_b128 v[180:183], v136
	ds_read_b128 v[184:187], v136 offset:1024
	ds_read_b128 v[188:191], v136 offset:2048
	ds_read_b128 v[192:195], v136 offset:3072
	s_add_u32 s82, s94, s2
	s_addc_u32 s83, s95, s3
	s_mov_b32 m0, s54
	v_lshl_add_u64 v[238:239], s[82:83], 0, v[138:139]
	ds_read_b128 v[196:199], v178 offset:32768
	ds_read_b128 v[200:203], v178 offset:33792
	ds_read_b128 v[204:207], v178 offset:34816
	ds_read_b128 v[208:211], v178 offset:35840
	ds_read_b128 v[212:215], v178 offset:36864
	ds_read_b128 v[216:219], v178 offset:37888
	ds_read_b128 v[220:223], v178 offset:38912
	ds_read_b128 v[224:227], v178 offset:39936
	global_load_lds_dwordx4 v[238:239], off
	v_lshl_add_u64 v[238:239], s[82:83], 0, v[142:143]
	s_mov_b32 m0, s55
	s_nop 0
	global_load_lds_dwordx4 v[238:239], off
	s_waitcnt vmcnt(8)
	s_waitcnt lgkmcnt(0)
	s_barrier
	s_setprio 1
	s_waitcnt lgkmcnt(0)
	v_mfma_f32_16x16x32_bf16 v[124:127], v[128:131], v[196:199], v[124:127]
	v_mfma_f32_16x16x32_bf16 v[120:123], v[152:155], v[196:199], v[120:123]
	v_mfma_f32_16x16x32_bf16 v[108:111], v[128:131], v[204:207], v[108:111]
	v_mfma_f32_16x16x32_bf16 v[104:107], v[152:155], v[204:207], v[104:107]
	v_mfma_f32_16x16x32_bf16 v[92:95], v[128:131], v[212:215], v[92:95]
	v_mfma_f32_16x16x32_bf16 v[88:91], v[152:155], v[212:215], v[88:91]
	v_mfma_f32_16x16x32_bf16 v[76:79], v[128:131], v[220:223], v[76:79]
	v_mfma_f32_16x16x32_bf16 v[72:75], v[152:155], v[220:223], v[72:75]
	v_mfma_f32_16x16x32_bf16 v[124:127], v[132:135], v[200:203], v[124:127]
	v_mfma_f32_16x16x32_bf16 v[120:123], v[156:159], v[200:203], v[120:123]
	v_mfma_f32_16x16x32_bf16 v[108:111], v[132:135], v[208:211], v[108:111]
	v_mfma_f32_16x16x32_bf16 v[104:107], v[156:159], v[208:211], v[104:107]
	v_mfma_f32_16x16x32_bf16 v[92:95], v[132:135], v[216:219], v[92:95]
	v_mfma_f32_16x16x32_bf16 v[88:91], v[156:159], v[216:219], v[88:91]
	v_mfma_f32_16x16x32_bf16 v[76:79], v[132:135], v[224:227], v[76:79]
	v_mfma_f32_16x16x32_bf16 v[72:75], v[156:159], v[224:227], v[72:75]
	s_setprio 0
	s_setprio 1
	v_mfma_f32_16x16x32_bf16 v[116:119], v[180:183], v[196:199], v[116:119]
	v_mfma_f32_16x16x32_bf16 v[112:115], v[188:191], v[196:199], v[112:115]
	v_mfma_f32_16x16x32_bf16 v[100:103], v[180:183], v[204:207], v[100:103]
	v_mfma_f32_16x16x32_bf16 v[96:99], v[188:191], v[204:207], v[96:99]
	v_mfma_f32_16x16x32_bf16 v[84:87], v[180:183], v[212:215], v[84:87]
	v_mfma_f32_16x16x32_bf16 v[80:83], v[188:191], v[212:215], v[80:83]
	v_mfma_f32_16x16x32_bf16 v[68:71], v[180:183], v[220:223], v[68:71]
	v_mfma_f32_16x16x32_bf16 v[64:67], v[188:191], v[220:223], v[64:67]
	v_mfma_f32_16x16x32_bf16 v[116:119], v[184:187], v[200:203], v[116:119]
	v_mfma_f32_16x16x32_bf16 v[112:115], v[192:195], v[200:203], v[112:115]
	v_mfma_f32_16x16x32_bf16 v[100:103], v[184:187], v[208:211], v[100:103]
	v_mfma_f32_16x16x32_bf16 v[96:99], v[192:195], v[208:211], v[96:99]
	v_mfma_f32_16x16x32_bf16 v[84:87], v[184:187], v[216:219], v[84:87]
	v_mfma_f32_16x16x32_bf16 v[80:83], v[192:195], v[216:219], v[80:83]
	v_mfma_f32_16x16x32_bf16 v[68:71], v[184:187], v[224:227], v[68:71]
	v_mfma_f32_16x16x32_bf16 v[64:67], v[192:195], v[224:227], v[64:67]
	s_setprio 0
	s_barrier
	s_add_i32 s7, s7, s51
	v_lshl_add_u64 v[160:161], v[160:161], 0, s[26:27]
	s_mov_b32 m0, s7
	ds_read_b128 v[196:199], v178 offset:49152
	ds_read_b128 v[200:203], v178 offset:50176
	ds_read_b128 v[204:207], v178 offset:51200
	ds_read_b128 v[208:211], v178 offset:52224
	ds_read_b128 v[212:215], v178 offset:53248
	ds_read_b128 v[216:219], v178 offset:54272
	ds_read_b128 v[220:223], v178 offset:55296
	ds_read_b128 v[224:227], v178 offset:56320
	global_load_lds_dwordx4 v[160:161], off
	v_lshl_add_u64 v[160:161], v[228:229], 0, s[26:27]
	s_add_i32 m0, s7, 0x2000
	s_add_i32 s7, vcc_hi, s51
	global_load_lds_dwordx4 v[160:161], off
	v_lshl_add_u64 v[160:161], v[230:231], 0, s[26:27]
	s_mov_b32 m0, s7
	s_nop 0
	global_load_lds_dwordx4 v[160:161], off
	v_lshl_add_u64 v[160:161], v[232:233], 0, s[26:27]
	s_add_i32 m0, s7, 0x2000
	s_nop 0
	global_load_lds_dwordx4 v[160:161], off
	v_lshl_add_u64 v[160:161], v[234:235], 0, s[26:27]
	s_mov_b32 m0, s57
	s_nop 0
	global_load_lds_dwordx4 v[160:161], off
	v_lshl_add_u64 v[160:161], v[236:237], 0, s[26:27]
	s_mov_b32 m0, s58
	s_nop 0
	global_load_lds_dwordx4 v[160:161], off
	s_waitcnt vmcnt(8)
	s_waitcnt lgkmcnt(0)
	s_barrier
	s_setprio 1
	s_waitcnt lgkmcnt(0)
	v_mfma_f32_16x16x32_bf16 v[60:63], v[128:131], v[196:199], v[60:63]
	v_mfma_f32_16x16x32_bf16 v[56:59], v[152:155], v[196:199], v[56:59]
	v_mfma_f32_16x16x32_bf16 v[44:47], v[128:131], v[204:207], v[44:47]
	v_mfma_f32_16x16x32_bf16 v[40:43], v[152:155], v[204:207], v[40:43]
	v_mfma_f32_16x16x32_bf16 v[28:31], v[128:131], v[212:215], v[28:31]
	v_mfma_f32_16x16x32_bf16 v[24:27], v[152:155], v[212:215], v[24:27]
	v_mfma_f32_16x16x32_bf16 v[12:15], v[128:131], v[220:223], v[12:15]
	v_mfma_f32_16x16x32_bf16 v[8:11], v[152:155], v[220:223], v[8:11]
	v_mfma_f32_16x16x32_bf16 v[60:63], v[132:135], v[200:203], v[60:63]
	v_mfma_f32_16x16x32_bf16 v[56:59], v[156:159], v[200:203], v[56:59]
	v_mfma_f32_16x16x32_bf16 v[44:47], v[132:135], v[208:211], v[44:47]
	v_mfma_f32_16x16x32_bf16 v[40:43], v[156:159], v[208:211], v[40:43]
	v_mfma_f32_16x16x32_bf16 v[28:31], v[132:135], v[216:219], v[28:31]
	v_mfma_f32_16x16x32_bf16 v[24:27], v[156:159], v[216:219], v[24:27]
	v_mfma_f32_16x16x32_bf16 v[12:15], v[132:135], v[224:227], v[12:15]
	v_mfma_f32_16x16x32_bf16 v[8:11], v[156:159], v[224:227], v[8:11]
	s_setprio 0
	s_setprio 1
	v_mfma_f32_16x16x32_bf16 v[52:55], v[180:183], v[196:199], v[52:55]
	v_mfma_f32_16x16x32_bf16 v[48:51], v[188:191], v[196:199], v[48:51]
	v_mfma_f32_16x16x32_bf16 v[36:39], v[180:183], v[204:207], v[36:39]
	v_mfma_f32_16x16x32_bf16 v[32:35], v[188:191], v[204:207], v[32:35]
	v_mfma_f32_16x16x32_bf16 v[20:23], v[180:183], v[212:215], v[20:23]
	v_mfma_f32_16x16x32_bf16 v[16:19], v[188:191], v[212:215], v[16:19]
	v_mfma_f32_16x16x32_bf16 v[4:7], v[180:183], v[220:223], v[4:7]
	v_mfma_f32_16x16x32_bf16 v[0:3], v[188:191], v[220:223], v[0:3]
	v_mfma_f32_16x16x32_bf16 v[52:55], v[184:187], v[200:203], v[52:55]
	v_mfma_f32_16x16x32_bf16 v[48:51], v[192:195], v[200:203], v[48:51]
	v_mfma_f32_16x16x32_bf16 v[36:39], v[184:187], v[208:211], v[36:39]
	v_mfma_f32_16x16x32_bf16 v[32:35], v[192:195], v[208:211], v[32:35]
	v_mfma_f32_16x16x32_bf16 v[20:23], v[184:187], v[216:219], v[20:23]
	v_mfma_f32_16x16x32_bf16 v[16:19], v[192:195], v[216:219], v[16:19]
	v_mfma_f32_16x16x32_bf16 v[4:7], v[184:187], v[224:227], v[4:7]
	v_mfma_f32_16x16x32_bf16 v[0:3], v[192:195], v[224:227], v[0:3]
	s_setprio 0
	s_barrier
	s_add_u32 s92, s92, 0x100
	s_addc_u32 s93, s93, 0
	s_add_u32 s96, s96, 0x100
	s_addc_u32 s97, s97, 0
	s_cmp_ge_u32 vcc_lo, s19
	s_mov_b32 s94, vcc_lo
	s_cbranch_scc0 .LBB0_150
	s_branch .Lkloop_done
.Lkloop_zero:
	v_mov_b32_e32 v0, 0
	v_mov_b32_e32 v1, v0
	v_mov_b32_e32 v2, v0
	v_mov_b32_e32 v3, v0
	v_mov_b32_e32 v4, v0
	v_mov_b32_e32 v5, v0
	v_mov_b32_e32 v6, v0
	v_mov_b32_e32 v7, v0
	v_mov_b32_e32 v16, v0
	v_mov_b32_e32 v17, v0
	v_mov_b32_e32 v18, v0
	v_mov_b32_e32 v19, v0
	v_mov_b32_e32 v20, v0
	v_mov_b32_e32 v21, v0
	v_mov_b32_e32 v22, v0
	v_mov_b32_e32 v23, v0
	v_mov_b32_e32 v32, v0
	v_mov_b32_e32 v33, v0
	v_mov_b32_e32 v34, v0
	v_mov_b32_e32 v35, v0
	v_mov_b32_e32 v36, v0
	v_mov_b32_e32 v37, v0
	v_mov_b32_e32 v38, v0
	v_mov_b32_e32 v39, v0
	v_mov_b32_e32 v48, v0
	v_mov_b32_e32 v49, v0
	v_mov_b32_e32 v50, v0
	v_mov_b32_e32 v51, v0
	v_mov_b32_e32 v52, v0
	v_mov_b32_e32 v53, v0
	v_mov_b32_e32 v54, v0
	v_mov_b32_e32 v55, v0
	v_mov_b32_e32 v8, v0
	v_mov_b32_e32 v9, v0
	v_mov_b32_e32 v10, v0
	v_mov_b32_e32 v11, v0
	v_mov_b32_e32 v12, v0
	v_mov_b32_e32 v13, v0
	v_mov_b32_e32 v14, v0
	v_mov_b32_e32 v15, v0
	v_mov_b32_e32 v24, v0
	v_mov_b32_e32 v25, v0
	v_mov_b32_e32 v26, v0
	v_mov_b32_e32 v27, v0
	v_mov_b32_e32 v28, v0
	v_mov_b32_e32 v29, v0
	v_mov_b32_e32 v30, v0
	v_mov_b32_e32 v31, v0
	v_mov_b32_e32 v40, v0
	v_mov_b32_e32 v41, v0
	v_mov_b32_e32 v42, v0
	v_mov_b32_e32 v43, v0
	v_mov_b32_e32 v44, v0
	v_mov_b32_e32 v45, v0
	v_mov_b32_e32 v46, v0
	v_mov_b32_e32 v47, v0
	v_mov_b32_e32 v56, v0
	v_mov_b32_e32 v57, v0
	v_mov_b32_e32 v58, v0
	v_mov_b32_e32 v59, v0
	v_mov_b32_e32 v60, v0
	v_mov_b32_e32 v61, v0
	v_mov_b32_e32 v62, v0
	v_mov_b32_e32 v63, v0
	v_mov_b32_e32 v64, v0
	v_mov_b32_e32 v65, v0
	v_mov_b32_e32 v66, v0
	v_mov_b32_e32 v67, v0
	v_mov_b32_e32 v68, v0
	v_mov_b32_e32 v69, v0
	v_mov_b32_e32 v70, v0
	v_mov_b32_e32 v71, v0
	v_mov_b32_e32 v80, v0
	v_mov_b32_e32 v81, v0
	v_mov_b32_e32 v82, v0
	v_mov_b32_e32 v83, v0
	v_mov_b32_e32 v84, v0
	v_mov_b32_e32 v85, v0
	v_mov_b32_e32 v86, v0
	v_mov_b32_e32 v87, v0
	v_mov_b32_e32 v96, v0
	v_mov_b32_e32 v97, v0
	v_mov_b32_e32 v98, v0
	v_mov_b32_e32 v99, v0
	v_mov_b32_e32 v100, v0
	v_mov_b32_e32 v101, v0
	v_mov_b32_e32 v102, v0
	v_mov_b32_e32 v103, v0
	v_mov_b32_e32 v112, v0
	v_mov_b32_e32 v113, v0
	v_mov_b32_e32 v114, v0
	v_mov_b32_e32 v115, v0
	v_mov_b32_e32 v116, v0
	v_mov_b32_e32 v117, v0
	v_mov_b32_e32 v118, v0
	v_mov_b32_e32 v119, v0
	v_mov_b32_e32 v72, v0
	v_mov_b32_e32 v73, v0
	v_mov_b32_e32 v74, v0
	v_mov_b32_e32 v75, v0
	v_mov_b32_e32 v76, v0
	v_mov_b32_e32 v77, v0
	v_mov_b32_e32 v78, v0
	v_mov_b32_e32 v79, v0
	v_mov_b32_e32 v88, v0
	v_mov_b32_e32 v89, v0
	v_mov_b32_e32 v90, v0
	v_mov_b32_e32 v91, v0
	v_mov_b32_e32 v92, v0
	v_mov_b32_e32 v93, v0
	v_mov_b32_e32 v94, v0
	v_mov_b32_e32 v95, v0
	v_mov_b32_e32 v104, v0
	v_mov_b32_e32 v105, v0
	v_mov_b32_e32 v106, v0
	v_mov_b32_e32 v107, v0
	v_mov_b32_e32 v108, v0
	v_mov_b32_e32 v109, v0
	v_mov_b32_e32 v110, v0
	v_mov_b32_e32 v111, v0
	v_mov_b32_e32 v120, v0
	v_mov_b32_e32 v121, v0
	v_mov_b32_e32 v122, v0
	v_mov_b32_e32 v123, v0
	v_mov_b32_e32 v124, v0
	v_mov_b32_e32 v125, v0
	v_mov_b32_e32 v126, v0
	v_mov_b32_e32 v127, v0

.LBB0_463:
	s_or_b64 exec, exec, s[28:29]
	s_and_b32 s39, s34, 3
	v_ashrrev_i32_e32 v70, 7, v16
	s_lshl_b32 s47, s39, 2
	v_add_u32_e32 v71, s47, v70
	v_lshl_add_u32 v0, v0, 4, v71
	v_readlane_b32 s80, v241, 56
	v_ashrrev_i32_e32 v1, 31, v0
	v_readlane_b32 s88, v240, 0
	v_readlane_b32 s89, v240, 1
	v_and_b32_e32 v72, 7, v16
	s_mov_b64 s[28:29], -1
	v_lshl_add_u64 v[0:1], v[0:1], 2, s[88:89]
	global_load_dword v1, v[0:1], off
	v_lshl_add_u32 v0, v16, 2, 0
	v_add_u32_e32 v2, 0x10000, v0
	v_lshlrev_b32_e32 v0, 3, v72
	v_lshlrev_b32_e32 v8, 4, v72
	v_lshl_add_u32 v17, v72, 12, 0
	s_andn2_b64 vcc, exec, s[0:1]
	v_and_b32_e32 v18, 24, v0
	v_or_b32_e32 v13, 1, v0
	v_bitop3_b32 v19, v0, 25, 1 bitop3:0xc8
	v_or_b32_e32 v14, 2, v0
	v_bitop3_b32 v20, v0, 26, 2 bitop3:0xc8
	v_or_b32_e32 v15, 3, v0
	v_bitop3_b32 v21, v0, 27, 3 bitop3:0xc8
	v_or_b32_e32 v26, 4, v0
	v_bitop3_b32 v22, v0, 28, 4 bitop3:0xc8
	v_or_b32_e32 v27, 5, v0
	v_bitop3_b32 v23, v0, 29, 5 bitop3:0xc8
	v_or_b32_e32 v28, 6, v0
	v_bitop3_b32 v24, v0, 30, 6 bitop3:0xc8
	v_or_b32_e32 v29, 7, v0
	v_bitop3_b32 v25, v0, 31, 7 bitop3:0xc8
	v_readlane_b32 s81, v241, 57
	v_readlane_b32 s82, v241, 58
	v_readlane_b32 s83, v241, 59
	v_readlane_b32 s84, v241, 60
	v_readlane_b32 s85, v241, 61
	v_readlane_b32 s86, v241, 62
	v_readlane_b32 s87, v241, 63
	v_readlane_b32 s90, v240, 2
	v_readlane_b32 s91, v240, 3
	v_readlane_b32 s92, v240, 4
	v_readlane_b32 s93, v240, 5
	v_readlane_b32 s94, v240, 6
	v_readlane_b32 s95, v240, 7
	s_cbranch_vccnz .LBB0_477
	v_readlane_b32 s28, v241, 46
	v_readlane_b32 s29, v241, 47
	v_readlane_b32 s30, v241, 48
	v_readlane_b32 s31, v241, 49
	v_readlane_b32 s0, v243, 32
	v_readlane_b32 s1, v243, 33
	v_lshrrev_b32_e32 v170, 3, v16
	v_and_b32_e32 v171, 7, v16
	v_bfe_u32 v173, v170, 1, 3
	v_xor_b32_e32 v173, v173, v171
	v_lshlrev_b32_e32 v173, 4, v173
	v_lshl_add_u32 v173, v170, 7, v173
	v_bfe_u32 v174, v170, 1, 1
	v_lshlrev_b32_e32 v174, 2, v174
	v_xor_b32_e32 v174, v174, v171
	v_lshlrev_b32_e32 v174, 4, v174
	v_lshl_add_u32 v174, v170, 7, v174
	v_add_u32_e32 v174, 0x8000, v174
	s_lshl_b32 s48, s39, 7
	s_add_u32 s0, s0, s48
	s_addc_u32 s1, s1, 0
	s_lshl_b32 s49, s38, 7
	v_add_u32_e32 v172, s49, v170
	v_lshlrev_b32_e32 v172, 10, v172
	s_lshl_b32 s48, s39, 8
	v_lshl_add_u32 v175, v171, 5, s48
	v_add_u32_e32 v172, v172, v175
	v_mov_b32_e32 v208, 0
	v_mov_b32_e32 v209, 0
	v_mov_b32_e32 v210, 0
	v_mov_b32_e32 v211, 0
	v_mov_b32_e32 v212, 0
	v_mov_b32_e32 v213, 0
	v_mov_b32_e32 v214, 0
	v_mov_b32_e32 v215, 0
	s_mov_b64 s[50:51], exec
	v_cmp_gt_u32_e32 vcc, 64, v16
	s_and_b64 exec, s[50:51], vcc
	s_cbranch_execz .Lswa_s_noload
	s_lshl_b32 s48, s38, 3
	s_addk_i32 s48, 0x4000
	v_add_u32_e32 v175, s48, v170
	v_lshlrev_b32_e32 v175, 10, v175
	v_lshl_add_u32 v175, v171, 4, v175
	global_load_dwordx4 v[208:211], v175, s[0:1]
	global_load_dwordx4 v[212:215], v175, s[0:1] offset:512
.Lswa_s_noload:
	s_mov_b64 exec, s[50:51]
	global_load_dwordx4 v[176:179], v172, s[28:29]
	global_load_dwordx4 v[180:183], v172, s[28:29] offset:16
	global_load_dwordx4 v[184:187], v172, s[30:31]
	global_load_dwordx4 v[188:191], v172, s[30:31] offset:16
	v_add_u32_e32 v172, 0x10000, v172
	global_load_dwordx4 v[192:195], v172, s[28:29]
	global_load_dwordx4 v[196:199], v172, s[28:29] offset:16
	global_load_dwordx4 v[200:203], v172, s[30:31]
	global_load_dwordx4 v[204:207], v172, s[30:31] offset:16
	v_readlane_b32 s48, v243, 52
	v_readlane_b32 s49, v243, 53
	s_lshl_b32 s0, s38, 3
	s_addk_i32 s0, 0x4000
	v_and_or_b32 v175, v16, 7, s0
	s_movk_i32 s1, 0xc00
	v_mul_lo_u32 v175, v175, s1
	v_bfe_u32 v172, v16, 3, 2
	s_lshl_b32 s0, s39, 2
	v_add_u32_e32 v172, s0, v172
	v_lshl_add_u32 v175, v172, 7, v175
	s_nop 1
	global_load_dword v228, v175, s[48:49]
	s_waitcnt vmcnt(5)
	v_cvt_pk_bf16_f32 v176, v176, v177
	v_cvt_pk_bf16_f32 v177, v178, v179
	v_cvt_pk_bf16_f32 v178, v180, v181
	v_cvt_pk_bf16_f32 v179, v182, v183
	v_cvt_pk_bf16_f32 v184, v184, v185
	v_cvt_pk_bf16_f32 v185, v186, v187
	v_cvt_pk_bf16_f32 v186, v188, v189
	v_cvt_pk_bf16_f32 v187, v190, v191
	ds_write_b128 v173, v[176:179]
	ds_write_b128 v174, v[184:187]
	s_waitcnt vmcnt(1)
	ds_write_b32 v2, v1
	v_cvt_pk_bf16_f32 v192, v192, v193
	v_cvt_pk_bf16_f32 v193, v194, v195
	v_cvt_pk_bf16_f32 v194, v196, v197
	v_cvt_pk_bf16_f32 v195, v198, v199
	v_cvt_pk_bf16_f32 v200, v200, v201
	v_cvt_pk_bf16_f32 v201, v202, v203
	v_cvt_pk_bf16_f32 v202, v204, v205
	v_cvt_pk_bf16_f32 v203, v206, v207
	ds_write_b128 v173, v[192:195] offset:8192
	ds_write_b128 v174, v[200:203] offset:8192
	v_cmp_gt_u32_e32 vcc, 0x100, v16
	s_and_b64 exec, s[50:51], vcc
	s_cbranch_execz .Lswa_s_done
	ds_write_b128 v173, v[208:211] offset:16384
	ds_write_b128 v174, v[212:215] offset:16384

.Lswa_p_write:
	v_readlane_b32 s50, v243, 52
	v_readlane_b32 s51, v243, 53
	v_bfe_u32 v175, v16, 6, 1
	v_lshlrev_b32_e32 v175, 6, v175
	v_and_or_b32 v175, v16, 31, v175
	s_lshl_b32 s0, s38, 13
	s_lshl_b32 s1, s46, 7
	s_or_b32 s0, s0, s1
	v_add_u32_e32 v175, s0, v175
	s_movk_i32 s1, 0xc00
	v_mul_lo_u32 v175, v175, s1
	v_lshl_add_u32 v175, v71, 7, v175
	v_add_u32_e32 v172, 0x18000, v175
	global_load_dword v228, v175, s[50:51]
	global_load_dword v229, v172, s[50:51]
	s_waitcnt vmcnt(2)
	ds_write_b32 v2, v1
	ds_write_b128 v173, v[176:179]
	ds_write_b128 v174, v[180:183]
	ds_write_b128 v173, v[184:187] offset:8192
	ds_write_b128 v174, v[188:191] offset:8192
	ds_write_b128 v173, v[192:195] offset:16384
	ds_write_b128 v174, v[196:199] offset:16384
	ds_write_b128 v173, v[200:203] offset:24576
	ds_write_b128 v174, v[204:207] offset:24576

.LBB0_542:
	v_cmp_gt_u32_e32 vcc, 64, v117
	s_or_b64 s[50:51], s[0:1], vcc
	s_mov_b64 s[48:49], exec
	s_and_b64 exec, s[48:49], s[50:51]
	s_cbranch_execz .Lmq_skip
	v_and_b32_e32 v224, 31, v117
	s_and_b64 vcc, exec, s[28:29]
	s_cbranch_vccz .Lmq_prompt
	s_lshl_b32 s50, s39, 3
	s_addk_i32 s50, 0x4000
	v_and_or_b32 v225, v117, 7, s50
	s_branch .Lmq_row
.Lmq_prompt:
	s_lshl_b32 s50, s39, 13
	s_or_b32 s50, s50, s46
	v_ashrrev_i32_e32 v225, 1, v117
	s_movk_i32 s51, 0xffe0
	v_and_or_b32 v225, v225, s51, v224
	v_add_u32_e32 v225, s50, v225
.Lmq_row:
	v_readlane_b32 s50, v240, 26
	s_lshl_b32 s51, s34, 7
	s_and_b32 s51, s51, 0x180
	s_lshl_b32 s51, s51, 1
	s_nop 0
	v_mul_lo_u32 v226, v225, s50
	v_lshl_add_u32 v226, v226, 1, s51
	v_lshrrev_b32_e32 v227, 1, v117
	v_and_b32_e32 v227, 16, v227
	v_add_u32_e32 v226, v226, v227
	global_load_dwordx4 v[80:83], v226, s[6:7]
	global_load_dwordx4 v[84:87], v226, s[6:7] offset:32
	global_load_dwordx4 v[88:91], v226, s[6:7] offset:64
	global_load_dwordx4 v[92:95], v226, s[6:7] offset:96
	global_load_dwordx4 v[96:99], v226, s[6:7] offset:128
	global_load_dwordx4 v[100:103], v226, s[6:7] offset:160
	global_load_dwordx4 v[104:107], v226, s[6:7] offset:192
	global_load_dwordx4 v[108:111], v226, s[6:7] offset:224
.Lmq_skip:
	s_mov_b64 exec, s[48:49]
	v_and_b32_e32 v2, 15, v117
	s_lshl_b32 s24, s34, 7
	v_lshlrev_b32_e32 v0, 3, v2
	s_lshl_b32 s30, s39, 8
	s_and_b32 s38, s24, 0x180
	s_mov_b64 s[24:25], -1
	s_andn2_b64 vcc, exec, s[28:29]
	v_and_b32_e32 v3, 24, v0
	v_or_b32_e32 v11, 1, v0
	v_bitop3_b32 v4, v0, 25, 1 bitop3:0xc8
	v_or_b32_e32 v12, 2, v0
	v_bitop3_b32 v5, v0, 26, 2 bitop3:0xc8
	v_or_b32_e32 v13, 3, v0
	v_bitop3_b32 v6, v0, 27, 3 bitop3:0xc8
	v_or_b32_e32 v14, 4, v0
	s_waitcnt lgkmcnt(0)
	v_bitop3_b32 v7, v0, 28, 4 bitop3:0xc8
	v_or_b32_e32 v15, 5, v0
	v_bitop3_b32 v8, v0, 29, 5 bitop3:0xc8
	v_or_b32_e32 v16, 6, v0
	v_bitop3_b32 v9, v0, 30, 6 bitop3:0xc8
	v_or_b32_e32 v17, 7, v0
	v_bitop3_b32 v10, v0, 31, 7 bitop3:0xc8
	s_cbranch_vccnz .LBB0_546
	v_lshrrev_b32_e32 v170, 4, v117
	v_and_b32_e32 v171, 15, v117
	v_add_u32_e32 v172, s30, v170
	v_lshlrev_b32_e32 v172, 11, v172
	s_lshl_b32 s24, s38, 2
	v_lshl_add_u32 v172, v171, 5, v172
	v_add_u32_e32 v172, s24, v172
	v_and_b32_e32 v173, 15, v170
	v_xor_b32_e32 v173, v173, v171
	v_lshlrev_b32_e32 v173, 4, v173
	v_lshl_add_u32 v173, v170, 8, v173
	v_and_b32_e32 v174, 3, v170
	v_lshlrev_b32_e32 v174, 2, v174
	v_xor_b32_e32 v174, v174, v171
	v_lshlrev_b32_e32 v174, 4, v174
	v_lshl_add_u32 v174, v170, 8, v174
	v_add_u32_e32 v174, 0x10000, v174
	global_load_dwordx4 v[176:179], v172, s[2:3]
	global_load_dwordx4 v[180:183], v172, s[2:3] offset:16
	global_load_dwordx4 v[184:187], v172, s[4:5]
	global_load_dwordx4 v[188:191], v172, s[4:5] offset:16
	v_add_u32_e32 v172, 0x10000, v172
	global_load_dwordx4 v[192:195], v172, s[2:3]
	global_load_dwordx4 v[196:199], v172, s[2:3] offset:16
	global_load_dwordx4 v[200:203], v172, s[4:5]
	global_load_dwordx4 v[204:207], v172, s[4:5] offset:16
	v_add_u32_e32 v172, 0x10000, v172
	global_load_dwordx4 v[208:211], v172, s[2:3]
	global_load_dwordx4 v[212:215], v172, s[2:3] offset:16
	global_load_dwordx4 v[216:219], v172, s[4:5]
	global_load_dwordx4 v[220:223], v172, s[4:5] offset:16
	v_add_u32_e32 v172, 0x10000, v172
	global_load_dwordx4 v[224:227], v172, s[2:3]
	global_load_dwordx4 v[228:231], v172, s[2:3] offset:16
	global_load_dwordx4 v[232:235], v172, s[4:5]
	global_load_dwordx4 v[236:239], v172, s[4:5] offset:16
	v_add_u32_e32 v172, 0x10000, v172
	s_waitcnt vmcnt(12)
	v_cvt_pk_bf16_f32 v176, v176, v177
	v_cvt_pk_bf16_f32 v177, v178, v179
	v_cvt_pk_bf16_f32 v178, v180, v181
	v_cvt_pk_bf16_f32 v179, v182, v183
	v_cvt_pk_bf16_f32 v184, v184, v185
	v_cvt_pk_bf16_f32 v185, v186, v187
	v_cvt_pk_bf16_f32 v186, v188, v189
	v_cvt_pk_bf16_f32 v187, v190, v191
	ds_write_b128 v173, v[176:179]
	ds_write_b128 v174, v[184:187]
	global_load_dwordx4 v[176:179], v172, s[2:3]
	global_load_dwordx4 v[180:183], v172, s[2:3] offset:16
	global_load_dwordx4 v[184:187], v172, s[4:5]
	global_load_dwordx4 v[188:191], v172, s[4:5] offset:16
	v_add_u32_e32 v172, 0x10000, v172
	s_waitcnt vmcnt(12)
	v_cvt_pk_bf16_f32 v192, v192, v193
	v_cvt_pk_bf16_f32 v193, v194, v195
	v_cvt_pk_bf16_f32 v194, v196, v197
	v_cvt_pk_bf16_f32 v195, v198, v199
	v_cvt_pk_bf16_f32 v200, v200, v201
	v_cvt_pk_bf16_f32 v201, v202, v203
	v_cvt_pk_bf16_f32 v202, v204, v205
	v_cvt_pk_bf16_f32 v203, v206, v207
	ds_write_b128 v173, v[192:195] offset:8192
	ds_write_b128 v174, v[200:203] offset:8192
	global_load_dwordx4 v[192:195], v172, s[2:3]
	global_load_dwordx4 v[196:199], v172, s[2:3] offset:16
	global_load_dwordx4 v[200:203], v172, s[4:5]
	global_load_dwordx4 v[204:207], v172, s[4:5] offset:16
	v_add_u32_e32 v172, 0x10000, v172
	s_waitcnt vmcnt(12)
	v_cvt_pk_bf16_f32 v208, v208, v209
	v_cvt_pk_bf16_f32 v209, v210, v211
	v_cvt_pk_bf16_f32 v210, v212, v213
	v_cvt_pk_bf16_f32 v211, v214, v215
	v_cvt_pk_bf16_f32 v216, v216, v217
	v_cvt_pk_bf16_f32 v217, v218, v219
	v_cvt_pk_bf16_f32 v218, v220, v221
	v_cvt_pk_bf16_f32 v219, v222, v223
	ds_write_b128 v173, v[208:211] offset:16384
	ds_write_b128 v174, v[216:219] offset:16384
	global_load_dwordx4 v[208:211], v172, s[2:3]
	global_load_dwordx4 v[212:215], v172, s[2:3] offset:16
	global_load_dwordx4 v[216:219], v172, s[4:5]
	global_load_dwordx4 v[220:223], v172, s[4:5] offset:16
	v_add_u32_e32 v172, 0x10000, v172
	s_waitcnt vmcnt(12)
	v_cvt_pk_bf16_f32 v224, v224, v225
	v_cvt_pk_bf16_f32 v225, v226, v227
	v_cvt_pk_bf16_f32 v226, v228, v229
	v_cvt_pk_bf16_f32 v227, v230, v231
	v_cvt_pk_bf16_f32 v232, v232, v233
	v_cvt_pk_bf16_f32 v233, v234, v235
	v_cvt_pk_bf16_f32 v234, v236, v237
	v_cvt_pk_bf16_f32 v235, v238, v239
	ds_write_b128 v173, v[224:227] offset:24576
	ds_write_b128 v174, v[232:235] offset:24576
	global_load_dwordx4 v[224:227], v172, s[2:3]
	global_load_dwordx4 v[228:231], v172, s[2:3] offset:16
	global_load_dwordx4 v[232:235], v172, s[4:5]
	global_load_dwordx4 v[236:239], v172, s[4:5] offset:16
	s_waitcnt vmcnt(12)
	v_cvt_pk_bf16_f32 v176, v176, v177
	v_cvt_pk_bf16_f32 v177, v178, v179
	v_cvt_pk_bf16_f32 v178, v180, v181
	v_cvt_pk_bf16_f32 v179, v182, v183
	v_cvt_pk_bf16_f32 v184, v184, v185
	v_cvt_pk_bf16_f32 v185, v186, v187
	v_cvt_pk_bf16_f32 v186, v188, v189
	v_cvt_pk_bf16_f32 v187, v190, v191
	ds_write_b128 v173, v[176:179] offset:32768
	ds_write_b128 v174, v[184:187] offset:32768
	s_waitcnt vmcnt(8)
	v_cvt_pk_bf16_f32 v192, v192, v193
	v_cvt_pk_bf16_f32 v193, v194, v195
	v_cvt_pk_bf16_f32 v194, v196, v197
	v_cvt_pk_bf16_f32 v195, v198, v199
	v_cvt_pk_bf16_f32 v200, v200, v201
	v_cvt_pk_bf16_f32 v201, v202, v203
	v_cvt_pk_bf16_f32 v202, v204, v205
	v_cvt_pk_bf16_f32 v203, v206, v207
	ds_write_b128 v173, v[192:195] offset:40960
	ds_write_b128 v174, v[200:203] offset:40960
	s_waitcnt vmcnt(4)
	v_cvt_pk_bf16_f32 v208, v208, v209
	v_cvt_pk_bf16_f32 v209, v210, v211
	v_cvt_pk_bf16_f32 v210, v212, v213
	v_cvt_pk_bf16_f32 v211, v214, v215
	v_cvt_pk_bf16_f32 v216, v216, v217
	v_cvt_pk_bf16_f32 v217, v218, v219
	v_cvt_pk_bf16_f32 v218, v220, v221
	v_cvt_pk_bf16_f32 v219, v222, v223
	ds_write_b128 v173, v[208:211] offset:49152
	ds_write_b128 v174, v[216:219] offset:49152
	s_waitcnt vmcnt(0)
	v_cvt_pk_bf16_f32 v224, v224, v225
	v_cvt_pk_bf16_f32 v225, v226, v227
	v_cvt_pk_bf16_f32 v226, v228, v229
	v_cvt_pk_bf16_f32 v227, v230, v231
	v_cvt_pk_bf16_f32 v232, v232, v233
	v_cvt_pk_bf16_f32 v233, v234, v235
	v_cvt_pk_bf16_f32 v234, v236, v237
	v_cvt_pk_bf16_f32 v235, v238, v239
	ds_write_b128 v173, v[224:227] offset:57344
	ds_write_b128 v174, v[232:235] offset:57344
	s_mov_b64 s[24:25], 0

.LBB0_554:
	v_readlane_b32 s28, v240, 26
	v_readlane_b32 s29, v240, 27
	s_lshl_b32 s34, s38, 1
	v_mad_i64_i32 v[0:1], s[28:29], s28, v116, 0
	v_lshl_add_u64 v[0:1], v[0:1], 1, s[6:7]
	v_lshrrev_b32_e32 v3, 1, v117
	v_lshl_add_u64 v[0:1], v[0:1], 0, s[34:35]
	v_and_b32_e32 v136, 16, v3
	v_lshl_add_u64 v[0:1], v[0:1], 0, v[136:137]
	v_bfe_u32 v120, v117, 5, 1
	v_lshlrev_b32_e32 v4, 8, v119
	v_and_b32_e32 v6, 64, v164
	v_bitop3_b32 v9, v120, v2, 10 bitop3:0x36
	v_xor_b32_e32 v5, 32, v164
	v_add_u32_e32 v6, 64, v6
	v_bitop3_b32 v8, v120, v2, 8 bitop3:0x36
	v_lshl_or_b32 v0, v9, 4, v4
	v_cmp_lt_i32_e32 vcc, v5, v6
	v_bitop3_b32 v7, v120, v2, 6 bitop3:0x36
	v_add_u32_e32 v125, 0, v0
	v_lshl_or_b32 v0, v8, 4, v4
	v_lshrrev_b32_e32 v3, 5, v117
	v_cndmask_b32_e32 v5, v164, v5, vcc
	v_bitop3_b32 v6, v120, v2, 4 bitop3:0x36
	v_add_u32_e32 v126, 0, v0
	v_lshl_or_b32 v0, v7, 4, v4
	v_lshlrev_b32_e32 v121, 2, v5
	v_bitop3_b32 v3, v3, v2, 1 bitop3:0x6c
	v_bitop3_b32 v5, v120, v2, 2 bitop3:0x36
	v_bitop3_b32 v10, v120, v2, 12 bitop3:0x36
	v_bitop3_b32 v2, v120, v2, 14 bitop3:0x36
	v_add_u32_e32 v127, 0, v0
	v_lshl_or_b32 v0, v6, 4, v4
	v_lshl_or_b32 v2, v2, 4, v4
	v_add_u32_e32 v128, 0, v0
	v_lshl_or_b32 v0, v5, 4, v4
	s_add_i32 s29, 0, 0x10000
	v_add_u32_e32 v123, 0, v2
	v_lshl_or_b32 v2, v10, 4, v4
	v_add_u32_e32 v129, 0, v0
	v_lshl_or_b32 v0, v3, 4, v4
	v_mov_b32_e32 v131, 0
	s_mov_b32 s28, 0
	v_lshl_add_u32 v122, v119, 9, s29
	v_add_u32_e32 v124, 0, v2
	v_add_u32_e32 v130, 0, v0
	v_mov_b32_e32 v132, 0xff800000
	v_mov_b32_e32 v0, 0
	v_mov_b32_e32 v1, v131
	v_mov_b32_e32 v2, v131
	v_mov_b32_e32 v3, v131
	v_mov_b32_e32 v4, v131
	v_mov_b32_e32 v5, v131
	v_mov_b32_e32 v6, v131
	v_mov_b32_e32 v7, v131
	v_mov_b32_e32 v8, v131
	v_mov_b32_e32 v9, v131
	v_mov_b32_e32 v10, v131
	v_mov_b32_e32 v11, v131
	v_mov_b32_e32 v12, v131
	v_mov_b32_e32 v13, v131
	v_mov_b32_e32 v14, v131
	v_mov_b32_e32 v15, v131
	v_mov_b32_e32 v16, 0
	v_mov_b32_e32 v17, v131
	v_mov_b32_e32 v18, v131
	v_mov_b32_e32 v19, v131
	v_mov_b32_e32 v20, v131
	v_mov_b32_e32 v21, v131
	v_mov_b32_e32 v22, v131
	v_mov_b32_e32 v23, v131
	v_mov_b32_e32 v24, v131
	v_mov_b32_e32 v25, v131
	v_mov_b32_e32 v26, v131
	v_mov_b32_e32 v27, v131
	v_mov_b32_e32 v28, v131
	v_mov_b32_e32 v29, v131
	v_mov_b32_e32 v30, v131
	v_mov_b32_e32 v31, v131
	v_mov_b32_e32 v32, 0
	v_mov_b32_e32 v33, v131
	v_mov_b32_e32 v34, v131
	v_mov_b32_e32 v35, v131
	v_mov_b32_e32 v36, v131
	v_mov_b32_e32 v37, v131
	v_mov_b32_e32 v38, v131
	v_mov_b32_e32 v39, v131
	v_mov_b32_e32 v40, v131
	v_mov_b32_e32 v41, v131
	v_mov_b32_e32 v42, v131
	v_mov_b32_e32 v43, v131
	v_mov_b32_e32 v44, v131
	v_mov_b32_e32 v45, v131
	v_mov_b32_e32 v46, v131
	v_mov_b32_e32 v47, v131
	v_mov_b32_e32 v48, 0
	v_mov_b32_e32 v49, v131
	v_mov_b32_e32 v50, v131
	v_mov_b32_e32 v51, v131
	v_mov_b32_e32 v52, v131
	v_mov_b32_e32 v53, v131
	v_mov_b32_e32 v54, v131
	v_mov_b32_e32 v55, v131
	v_mov_b32_e32 v56, v131
	v_mov_b32_e32 v57, v131
	v_mov_b32_e32 v58, v131
	v_mov_b32_e32 v59, v131
	v_mov_b32_e32 v60, v131
	v_mov_b32_e32 v61, v131
	v_mov_b32_e32 v62, v131
	v_mov_b32_e32 v63, v131
	v_and_b32_e32 v170, 63, v117
	v_bfe_u32 v171, v170, 2, 2
	v_and_b32_e32 v172, 3, v170
	v_lshlrev_b32_e32 v173, 8, v171
	v_lshl_add_u32 v173, v172, 3, v173
	v_bfe_u32 v172, v170, 4, 1
	v_lshl_add_u32 v173, v172, 5, v173
	v_lshrrev_b32_e32 v172, 5, v170
	v_lshl_add_u32 v173, v172, 10, v173
	v_add_u32_e32 v173, 0x10000, v173
	v_lshl_add_u32 v174, v171, 6, v173
	v_xor_b32_e32 v170, 1, v171
	v_lshl_add_u32 v175, v170, 6, v173
	v_xor_b32_e32 v170, 2, v171
	v_lshl_add_u32 v176, v170, 6, v173
	v_xor_b32_e32 v170, 3, v171
	v_lshl_add_u32 v177, v170, 6, v173

.LBB0_656:
	v_readlane_b32 s2, v242, 24
	v_readlane_b32 s3, v242, 25
	s_mov_b64 s[4:5], -1
	s_nop 4
	global_load_dword v0, v137, s[2:3] sc1
	global_load_dword v1, v137, s[2:3] offset:256 sc1
	global_load_dword v2, v137, s[2:3] offset:512 sc1
	global_load_dword v3, v137, s[2:3] offset:768 sc1
	global_load_dword v4, v137, s[2:3] offset:1024 sc1
	global_load_dword v5, v137, s[2:3] offset:1280 sc1
	global_load_dword v6, v137, s[2:3] offset:1536 sc1
	global_load_dword v7, v137, s[2:3] offset:1792 sc1
	global_load_dword v8, v137, s[2:3] offset:2048 sc1
	global_load_dword v9, v137, s[2:3] offset:2304 sc1
	global_load_dword v10, v137, s[2:3] offset:2560 sc1
	global_load_dword v11, v137, s[2:3] offset:2816 sc1
	global_load_dword v12, v137, s[2:3] offset:3072 sc1
	global_load_dword v13, v137, s[2:3] offset:3328 sc1
	global_load_dword v14, v137, s[2:3] offset:3584 sc1
	global_load_dword v15, v137, s[2:3] offset:3840 sc1
	s_waitcnt vmcnt(0)
	s_mov_b64 s[2:3], -1
	v_add_u32_e32 v16, v1, v0
	v_add_u32_e32 v16, v16, v2
	v_add_u32_e32 v16, v16, v3
	v_add_u32_e32 v16, v16, v4
	v_add_u32_e32 v16, v16, v5
	v_add_u32_e32 v16, v16, v6
	v_add_u32_e32 v16, v16, v7
	v_add_u32_e32 v16, v16, v8
	v_add_u32_e32 v16, v16, v9
	v_add_u32_e32 v16, v16, v10
	v_add_u32_e32 v16, v16, v11
	v_add_u32_e32 v16, v16, v12
	v_add_u32_e32 v16, v16, v13
	v_add_u32_e32 v16, v16, v14
	v_add_u32_e32 v16, v16, v15
	v_cmp_eq_u32_e32 vcc, s8, v16
	s_cbranch_vccnz .LBB0_655
	s_and_b32 s2, s9, 0xff
	s_cmp_eq_u32 s2, 0
	s_mov_b64 s[2:3], -1
	s_mov_b64 s[6:7], -1
	s_sleep 1
	s_cbranch_scc0 .LBB0_660
	v_readlane_b32 s2, v242, 22
	v_readlane_b32 s3, v242, 23
	s_nop 4
	global_load_dword v16, v137, s[2:3] sc1
	s_waitcnt vmcnt(0)
	v_cmp_eq_u32_e32 vcc, 0, v16
	s_cbranch_vccnz .LBB0_662
	s_mov_b64 s[6:7], 0
	s_mov_b64 s[2:3], -1
